# PH12 mid-epilogue vmcnt(0) drain relaxed to vmcnt(12) (on v41)
# baseline (speedup 1.0000x reference)
; __device__ __forceinline__ u32x4 pack8(f32x4 a, f32x4 b) { u32x4 w; w.x = pk2(a[0], a[1]); w.y = pk2(a[2], a[3]); w.z = pk2(b[0], b[1]); w.w = pk2(b[2], b[3]); return w; }
;     __device__ __forceinline__ void operator()(const Acc& acc, const pg8::Unit& u, int wid) const {
;     ...
;                 const int row = row0 + ai * 128 + m * 16; float sq = 0.f;
;                 const float rr = ssq2 ? __builtin_amdgcn_rcpf(r2[ai * 4 + m] * (1.f / 1024.f) + EPS) : 1.f;
; #pragma unroll
;                 for (int bj = 0; bj < 2; ++bj) {
;                     const u32x4 b4 = bv[ai][m][bj];
;                     const f32x4 o0 = (f32x4){bflo(b4.x), bfhi(b4.x), bflo(b4.y), bfhi(b4.y)} + acc[ai][bj][m][0] * rr;
;                     const f32x4 o1 = (f32x4){bflo(b4.z), bfhi(b4.z), bflo(b4.w), bfhi(b4.w)} + acc[ai][bj][m][1] * rr;
;                     *(u32x4*)(hb + (size_t)row * 1024 + col0 + bj * 128) = pack8(o0, o1);
;                     sq += (o0[0] * o0[0] + o0[1] * o0[1]) + (o0[2] * o0[2] + o0[3] * o0[3]) + (o1[0] * o1[0] + o1[1] * o1[1]) + (o1[2] * o1[2] + o1[3] * o1[3]);
;                 }
;                 if (ssq_out) { sq += __shfl_xor(sq, 16); sq += __shfl_xor(sq, 32); if (fq == 0) atomicAdd(ssq_out + row, sq); }
.LBB0_570:
	s_or_b64 exec, exec, s[0:1]
	v_fmamk_f32 v32, v248, 0x3a800000, v245
	v_rcp_f32_e32 v32, v32
	s_waitcnt vmcnt(12)
	v_lshlrev_b32_e32 v34, 16, v132
	v_and_b32_e32 v35, 0xffff0000, v132
	v_lshlrev_b32_e32 v36, 16, v133
	v_and_b32_e32 v37, 0xffff0000, v133
	v_lshlrev_b32_e32 v40, 16, v125
	v_and_b32_e32 v41, 0xffff0000, v125
	s_waitcnt lgkmcnt(0)
	v_pk_fma_f32 v[30:31], v[30:31], v[32:33], v[36:37] op_sel_hi:[1,0,1]
	v_pk_fma_f32 v[28:29], v[28:29], v[32:33], v[34:35] op_sel_hi:[1,0,1]
	v_lshlrev_b32_e32 v34, 16, v134
	v_and_b32_e32 v35, 0xffff0000, v134
	v_lshlrev_b32_e32 v38, 16, v124
	v_and_b32_e32 v39, 0xffff0000, v124
	v_pk_fma_f32 v[22:23], v[22:23], v[32:33], v[40:41] op_sel_hi:[1,0,1]
	v_lshlrev_b32_e32 v40, 16, v127
	v_and_b32_e32 v41, 0xffff0000, v127
	v_lshlrev_b32_e32 v36, 16, v135
	v_and_b32_e32 v37, 0xffff0000, v135
	v_pk_fma_f32 v[34:35], v[24:25], v[32:33], v[34:35] op_sel_hi:[1,0,1]
	v_pk_fma_f32 v[20:21], v[20:21], v[32:33], v[38:39] op_sel_hi:[1,0,1]
	v_lshlrev_b32_e32 v38, 16, v126
	v_and_b32_e32 v39, 0xffff0000, v126
	v_pk_fma_f32 v[40:41], v[18:19], v[32:33], v[40:41] op_sel_hi:[1,0,1]
	v_mul_f32_e32 v18, v29, v29
	v_mul_f32_e32 v19, v31, v31
	v_pk_fma_f32 v[36:37], v[26:27], v[32:33], v[36:37] op_sel_hi:[1,0,1]
	v_pk_fma_f32 v[32:33], v[16:17], v[32:33], v[38:39] op_sel_hi:[1,0,1]
	v_mul_f32_e32 v17, v35, v35
	v_fmac_f32_e32 v18, v28, v28
	v_fmac_f32_e32 v19, v30, v30
	v_cvt_pk_bf16_f32 v24, v28, v29
	v_mul_f32_e32 v16, v37, v37
	v_fmac_f32_e32 v17, v34, v34
	v_add_f32_e32 v18, v18, v19
	v_mul_f32_e32 v19, v21, v21
	v_mul_f32_e32 v28, v23, v23
	v_fmac_f32_e32 v16, v36, v36
	v_add_f32_e32 v17, v17, v18
	v_mul_f32_e32 v18, v33, v33
	v_fmac_f32_e32 v19, v20, v20
	v_fmac_f32_e32 v28, v22, v22
	v_add_f32_e32 v16, v16, v17
	v_mul_f32_e32 v17, v41, v41
	v_fmac_f32_e32 v18, v32, v32
	v_add_f32_e32 v19, v19, v28
	v_fmac_f32_e32 v17, v40, v40
	v_add_f32_e32 v18, v18, v19
	v_add_f32_e32 v17, v17, v18
	v_add_f32_e32 v19, v16, v17
	v_cvt_pk_bf16_f32 v25, v30, v31
	ds_bpermute_b32 v30, v112, v19
	v_lshlrev_b64 v[16:17], 11, v[210:211]
	v_lshl_add_u64 v[16:17], s[42:43], 0, v[16:17]
	v_lshl_add_u64 v[28:29], v[204:205], 1, v[16:17]
	v_cvt_pk_bf16_f32 v26, v34, v35
	s_waitcnt lgkmcnt(0)
	v_add_f32_e32 v16, v19, v30
	ds_bpermute_b32 v17, v113, v16
	v_cvt_pk_bf16_f32 v27, v36, v37
	v_cvt_pk_bf16_f32 v18, v20, v21
	v_cvt_pk_bf16_f32 v19, v22, v23
	v_cvt_pk_bf16_f32 v20, v32, v33
	v_cvt_pk_bf16_f32 v21, v40, v41
	flat_store_dwordx4 v[28:29], v[24:27]
	flat_store_dwordx4 v[28:29], v[18:21] offset:256
	s_and_saveexec_b64 s[0:1], vcc
	s_cbranch_execz .LBB0_572
	v_lshl_add_u64 v[18:19], v[210:211], 2, s[60:61]
	s_waitcnt lgkmcnt(0)
	v_add_f32_e32 v16, v16, v17
	flat_atomic_add_f32 v[18:19], v16

; __device__ __forceinline__ u32x4 pack8(f32x4 a, f32x4 b) { u32x4 w; w.x = pk2(a[0], a[1]); w.y = pk2(a[2], a[3]); w.z = pk2(b[0], b[1]); w.w = pk2(b[2], b[3]); return w; }
;     __device__ __forceinline__ void operator()(const Acc& acc, const pg8::Unit& u, int wid) const {
;     ...
;                 const int row = row0 + ai * 128 + m * 16; float sq = 0.f;
;                 const float rr = ssq2 ? __builtin_amdgcn_rcpf(r2[ai * 4 + m] * (1.f / 1024.f) + EPS) : 1.f;
; #pragma unroll
;                 for (int bj = 0; bj < 2; ++bj) {
;                     const u32x4 b4 = bv[ai][m][bj];
;                     const f32x4 o0 = (f32x4){bflo(b4.x), bfhi(b4.x), bflo(b4.y), bfhi(b4.y)} + acc[ai][bj][m][0] * rr;
;                     const f32x4 o1 = (f32x4){bflo(b4.z), bfhi(b4.z), bflo(b4.w), bfhi(b4.w)} + acc[ai][bj][m][1] * rr;
;                     *(u32x4*)(hb + (size_t)row * 1024 + col0 + bj * 128) = pack8(o0, o1);
;                     sq += (o0[0] * o0[0] + o0[1] * o0[1]) + (o0[2] * o0[2] + o0[3] * o0[3]) + (o1[0] * o1[0] + o1[1] * o1[1]) + (o1[2] * o1[2] + o1[3] * o1[3]);
;                 }
;                 if (ssq_out) { sq += __shfl_xor(sq, 16); sq += __shfl_xor(sq, 32); if (fq == 0) atomicAdd(ssq_out + row, sq); }
.LBB0_1260:
	s_or_b64 exec, exec, s[0:1]
	v_fmamk_f32 v32, v247, 0x3a800000, v245
	v_rcp_f32_e32 v32, v32
	s_waitcnt vmcnt(12)
	v_lshlrev_b32_e32 v34, 16, v132
	v_and_b32_e32 v35, 0xffff0000, v132
	v_lshlrev_b32_e32 v36, 16, v133
	v_and_b32_e32 v37, 0xffff0000, v133
	v_lshlrev_b32_e32 v40, 16, v125
	v_and_b32_e32 v41, 0xffff0000, v125
	s_waitcnt lgkmcnt(0)
	v_pk_fma_f32 v[30:31], v[30:31], v[32:33], v[36:37] op_sel_hi:[1,0,1]
	v_pk_fma_f32 v[28:29], v[28:29], v[32:33], v[34:35] op_sel_hi:[1,0,1]
	v_lshlrev_b32_e32 v34, 16, v134
	v_and_b32_e32 v35, 0xffff0000, v134
	v_lshlrev_b32_e32 v38, 16, v124
	v_and_b32_e32 v39, 0xffff0000, v124
	v_pk_fma_f32 v[22:23], v[22:23], v[32:33], v[40:41] op_sel_hi:[1,0,1]
	v_lshlrev_b32_e32 v40, 16, v127
	v_and_b32_e32 v41, 0xffff0000, v127
	v_lshlrev_b32_e32 v36, 16, v135
	v_and_b32_e32 v37, 0xffff0000, v135
	v_pk_fma_f32 v[34:35], v[24:25], v[32:33], v[34:35] op_sel_hi:[1,0,1]
	v_pk_fma_f32 v[20:21], v[20:21], v[32:33], v[38:39] op_sel_hi:[1,0,1]
	v_lshlrev_b32_e32 v38, 16, v126
	v_and_b32_e32 v39, 0xffff0000, v126
	v_pk_fma_f32 v[40:41], v[18:19], v[32:33], v[40:41] op_sel_hi:[1,0,1]
	v_mul_f32_e32 v18, v29, v29
	v_mul_f32_e32 v19, v31, v31
	v_pk_fma_f32 v[36:37], v[26:27], v[32:33], v[36:37] op_sel_hi:[1,0,1]
	v_pk_fma_f32 v[32:33], v[16:17], v[32:33], v[38:39] op_sel_hi:[1,0,1]
	v_mul_f32_e32 v17, v35, v35
	v_fmac_f32_e32 v18, v28, v28
	v_fmac_f32_e32 v19, v30, v30
	v_cvt_pk_bf16_f32 v24, v28, v29
	v_mul_f32_e32 v16, v37, v37
	v_fmac_f32_e32 v17, v34, v34
	v_add_f32_e32 v18, v18, v19
	v_mul_f32_e32 v19, v21, v21
	v_mul_f32_e32 v28, v23, v23
	v_fmac_f32_e32 v16, v36, v36
	v_add_f32_e32 v17, v17, v18
	v_mul_f32_e32 v18, v33, v33
	v_fmac_f32_e32 v19, v20, v20
	v_fmac_f32_e32 v28, v22, v22
	v_add_f32_e32 v16, v16, v17
	v_mul_f32_e32 v17, v41, v41
	v_fmac_f32_e32 v18, v32, v32
	v_add_f32_e32 v19, v19, v28
	v_fmac_f32_e32 v17, v40, v40
	v_add_f32_e32 v18, v18, v19
	v_add_f32_e32 v17, v17, v18
	v_add_f32_e32 v19, v16, v17
	v_cvt_pk_bf16_f32 v25, v30, v31
	ds_bpermute_b32 v30, v112, v19
	v_lshlrev_b64 v[16:17], 11, v[210:211]
	v_lshl_add_u64 v[16:17], s[42:43], 0, v[16:17]
	v_lshl_add_u64 v[28:29], v[204:205], 1, v[16:17]
	v_cvt_pk_bf16_f32 v26, v34, v35
	s_waitcnt lgkmcnt(0)
	v_add_f32_e32 v16, v19, v30
	ds_bpermute_b32 v17, v113, v16
	v_cvt_pk_bf16_f32 v27, v36, v37
	v_cvt_pk_bf16_f32 v18, v20, v21
	v_cvt_pk_bf16_f32 v19, v22, v23
	v_cvt_pk_bf16_f32 v20, v32, v33
	v_cvt_pk_bf16_f32 v21, v40, v41
	flat_store_dwordx4 v[28:29], v[24:27]
	flat_store_dwordx4 v[28:29], v[18:21] offset:256
	s_and_saveexec_b64 s[0:1], vcc
	s_cbranch_execz .LBB0_1262
	v_lshl_add_u64 v[18:19], v[210:211], 2, s[36:37]
	s_waitcnt lgkmcnt(0)
	v_add_f32_e32 v16, v16, v17
	flat_atomic_add_f32 v[18:19], v16
